# GEMM1 call setup: short-conv weight LDS copy made non-blocking (loads issued before the first tile loads, waited with vmcnt(8) and written to LDS just before the first stage wait)
# speedup vs baseline: 1.0008x; 1.0008x over previous
; __device__ __forceinline__ int opaque_nblk() { int g = (int)gridDim.x; asm volatile("" : "+s"(g)); return g; }
; __global__ void __launch_bounds__(512, 2) fwd_megakernel(Params Pval) {
;     ...
;                 const int ngi = (sub == 0) ? 2 : 1;
;                 for (int gi = 0; gi < ngi; ++gi) {
;                     pg8::Gemm g; EpiAll E{0, layer, ws, P->out};
;                     if (sub == 0 && gi == 0) {
;                         g = pg8::Gemm{(const bf16_t*)(ws + OFF_XB), (const bf16_t*)(ws + OFF_BTIN) + (size_t)layer * NIN * 1024, MTOK, NIN, 1024, 1024};
;                         E.mode = 0;
;                     } else if (sub == 0) {
;                         g = pg8::Gemm{(const bf16_t*)(ws + OFF_PB) + (size_t)layer * MTOK * 256, (const bf16_t*)(ws + OFF_BTP) + (size_t)layer * 1024 * 256, MTOK, 1024, 256, 256};
;                         E.mode = 1;
;                     } else if (sub == 4) {
;                         g = pg8::Gemm{(const bf16_t*)(ws + OFF_PROJ) + COL_Z, (const bf16_t*)(ws + OFF_BTOUT) + (size_t)layer * 1024 * 2048, MTOK, 1024, 2048, PW};
;                         E.mode = 2;
;                     } else {
;                         g = pg8::Gemm{(const bf16_t*)(ws + OFF_PROJ), (const bf16_t*)(ws + OFF_BTG) + (size_t)layer * 1024 * 1024, MTOK, 1024, 1024, 1024};
;                         E.mode = 3;
;                     }
;                     S.init(g.M, g.N, opaque_nblk(), blockIdx.x); pg8::gemm_phase(lds, g, S, E);
.LBB0_105:
	s_cmp_lg_u32 s1, 0
	s_cbranch_scc1 .Lscw_skip
	s_load_dwordx2 s[16:17], s[36:37], 0x58
	s_andn2_b32 s18, 0x3000, s94
	v_mul_u32_u24_e32 v1, 24, v0
	s_waitcnt lgkmcnt(0)
	s_add_u32 s16, s16, s18
	s_addc_u32 s17, s17, 0
	v_mov_b32_e32 v236, v1
	global_load_dwordx2 v[230:231], v236, s[16:17]
	global_load_dwordx2 v[232:233], v236, s[16:17] offset:8
	global_load_dwordx2 v[234:235], v236, s[16:17] offset:16

; __device__ __forceinline__ int opaque_tid() { int t = threadIdx.x; asm volatile("" : "+v"(t)); return t; }
; #define PG8_STAGE(bufoff, gbase, voff) do { _Pragma("unroll") for (int _i = 0; _i < 2; ++_i) \
;         __builtin_amdgcn_global_load_lds((const unsigned*)((const char*)(gbase) + (voff)[_i]), (LAS unsigned*)(lds + (bufoff) + ldsw + _i * 8192), 16, 0, 0); } while (0)
; #define PG8_WAIT_V(n) asm volatile("s_waitcnt vmcnt(" #n ")" ::: "memory")
; #define PG8_BAR __builtin_amdgcn_s_barrier()
; template <class Epi>
; __device__ __forceinline__ void gemm_phase(LAS unsigned char* lds, const Gemm g, const StaticOrder& S, const Epi& E) {
;     const int tid = opaque_tid(), wid = __builtin_amdgcn_readfirstlane(tid >> 6), lane = tid & 63, wr = wid >> 2, wc = wid & 3, fr = lane & 15, fq = lane >> 4;
;     const int K = g.K, nt = K / BK, lda = g.lda;
;     unsigned voffA[2], voffB[2];
; #pragma unroll
;     for (int i = 0; i < 2; ++i) { int R, C; stage_rc(tid * 16 + i * 8192, R, C); const int Rb = Epi::PERM ? ((R & ~31) + perm32(R & 31)) : R;
;         voffA[i] = (unsigned)(R * lda + C) * 2u; voffB[i] = (unsigned)(Rb * K + C) * 2u; }
;     const size_t kstep = (size_t)(BK * 2);
;     const size_t hstepA = (size_t)HALF * lda * 2, hstepB = (size_t)HALF * K * 2;
;     const size_t tstepA = 2 * hstepA, tstepB = 2 * hstepB;
;     const unsigned ldsw = (unsigned)wid * 1024u;
;     const int aoff = lds_byte(wr * 64 + fr, fq * 8), boff = lds_byte(wc * 32 + fr, fq * 8);
;     ...
;     PG8_STAGE(PG8_SB(0, 0), cB, voffB); PG8_STAGE(PG8_SA(0, 0), cA, voffA); PG8_STAGE(PG8_SB(0, 1), cB + hstepB, voffB); PG8_STAGE(PG8_SA(0, 1), cA + hstepA, voffA);
;     if (wr == 1) PG8_BAR;
;     PG8_WAIT_V(4); PG8_BAR;
;     PG8_STAGE(PG8_SB(1, 0), cB + kstep, voffB); PG8_STAGE(PG8_SA(1, 0), cA + kstep, voffA); PG8_STAGE(PG8_SB(1, 1), cB + hstepB + kstep, voffB);
;     PG8_WAIT_V(6); PG8_BAR;
.Lprio_done:
	s_add_i32 m0, s39, 0x18000
	v_lshl_add_u64 v[12:13], v[12:13], 0, s[88:89]
	s_cmp_lg_u32 s1, 0
	s_cbranch_scc1 .Lscw_w
	v_add_u32_e32 v236, 0x20800, v236
	s_waitcnt vmcnt(8)
	ds_write_b64 v236, v[230:231]
	ds_write_b64 v236, v[232:233] offset:8
	ds_write_b64 v236, v[234:235] offset:16
.Lscw_w:
	s_waitcnt vmcnt(4)
	s_barrier
	global_load_lds_dwordx4 v[12:13], off
	v_lshl_add_u64 v[10:11], v[10:11], 0, s[88:89]
	s_add_i32 m0, s39, 0x1a000
	s_add_i32 s60, s39, 0x8000
	global_load_lds_dwordx4 v[10:11], off
	v_lshl_add_u64 v[8:9], v[8:9], 0, s[88:89]
	s_mov_b32 m0, s60
	s_add_i32 s61, s39, 0xa000
	global_load_lds_dwordx4 v[8:9], off
	v_lshl_add_u64 v[6:7], v[6:7], 0, s[88:89]
	s_mov_b32 m0, s61
	v_lshl_add_u64 v[4:5], v[4:5], 0, s[88:89]
	global_load_lds_dwordx4 v[6:7], off
	s_add_i32 m0, s39, 0x1c000
	v_lshl_add_u64 v[2:3], v[2:3], 0, s[88:89]
	global_load_lds_dwordx4 v[4:5], off
	s_add_i32 m0, s39, 0x1e000
	v_bfe_u32 v4, v0, 4, 2
	global_load_lds_dwordx4 v[2:3], off
	v_and_b32_e32 v3, 15, v0
	v_lshlrev_b32_e32 v2, 4, v4
	v_lshl_or_b32 v171, s17, 6, v3
	v_lshl_or_b32 v6, v3, 6, v2
	v_lshlrev_b32_e32 v3, 2, v3
	s_and_b32 s30, s18, 3
	s_lshr_b32 s16, s7, 6
	s_lshl_b32 s7, s17, 13
	v_and_b32_e32 v7, 32, v3
	v_bitop3_b32 v8, v6, s7, v7 bitop3:0xde
	s_lshl_b32 s7, s30, 12
	v_bitop3_b32 v225, v6, s7, v7 bitop3:0xde
	s_lshl_b32 s7, s17, 8
	s_add_i32 s19, 0, 0x20000
	s_add_i32 s7, s19, s7
	s_add_i32 s17, s16, -2
	s_cmp_lt_i32 s18, 4
	v_add_u32_e32 v226, s7, v3
	s_cselect_b64 s[24:25], -1, 0
	s_and_b32 s7, s79, 0x3fffffc0
	s_lshl_b32 s7, s7, 2
	s_add_i32 s18, s19, s7
	s_cmp_eq_u32 s30, 0
	s_cselect_b64 s[26:27], -1, 0
	s_lshl_b32 s33, s6, 4
	s_lshl_b32 s6, s6, 3
	v_lshl_add_u64 v[180:181], v[0:1], 2, s[62:63]
	v_cvt_f32_ubyte0_e32 v0, s6
	v_cmp_gt_u32_e32 vcc, 2, v4
	v_rcp_iflag_f32_e32 v6, v0
	s_and_b64 s[26:27], s[26:27], vcc
	s_ashr_i32 s19, s53, 31
	s_lshl_b32 s7, s30, 6
	s_add_u32 s28, s98, s7
	s_addc_u32 s29, s99, 0
	v_mov_b32_e32 v3, v169
	v_lshl_add_u64 v[182:183], s[28:29], 0, v[2:3]
	v_mul_f32_e32 v2, 0x4f7ffffe, v6
	v_cvt_u32_f32_e32 v2, v2
	v_readlane_b32 s28, v255, 20
	v_lshlrev_b32_e32 v0, 5, v4
	v_mov_b32_e32 v1, v169
	v_readlane_b32 s29, v255, 21
	s_sub_i32 s7, 0, s6
	s_waitcnt vmcnt(6)
	v_lshlrev_b32_e32 v5, 3, v4
	v_lshl_add_u64 v[184:185], s[28:29], 0, v[0:1]
	v_add_u32_e32 v0, v16, v14
	v_readfirstlane_b32 s28, v2
	v_add_lshl_u32 v0, v0, v15, 1
	s_mul_i32 s7, s7, s28
	v_lshl_add_u64 v[186:187], s[74:75], 0, v[0:1]
	v_add_u32_e32 v0, v19, v17
	s_mul_hi_u32 s7, s28, s7
	v_add_lshl_u32 v0, v0, v18, 1
	s_mov_b32 s68, 0
	v_cmp_eq_u32_e64 s[40:41], 0, v4
	s_mov_b32 s23, s21
	v_lshl_or_b32 v227, s30, 5, v5
	s_add_i32 s7, s28, s7
	v_lshl_add_u64 v[188:189], s[74:75], 0, v[0:1]
	v_add_u32_e32 v228, 0, v8
	s_barrier
	s_branch .LBB0_109
